# v17 + hand-written lin staging loop + hand-written round A (hoisted a_up weight loads, A fragments shared across column tiles, 8 interleaved sigmoid chains); same bf16 MFMA / f32 accumulate
# speedup vs baseline: 1.0270x; 1.0046x over previous
; #define LAS __attribute__((address_space(3)))
; __device__ __forceinline__ unsigned pk2(float lo, float hi) { f32x2 f = {lo, hi}; bf16x2_t v = __builtin_convertvector(f, bf16x2_t); return __builtin_bit_cast(unsigned, v); }
; __device__ __forceinline__ float sigm(float x) { return __builtin_amdgcn_rcpf(1.0f + __expf(-x)); }
; __device__ __forceinline__ void prep_tile64(LAS unsigned char* lds, const Params& P, const MixBufs& B, const bf16_t* sw, int layer, int L, int tile) {
;     ...
; #pragma unroll 3
;     for (int i6 = 0; i6 < 6; ++i6) {
;         const int it = tid + 512 * i6;
;         const int t = it / 48, cg8 = it % 48, tl = t0 + t, pos = tl % L, col = PC_RLOW + cg8 * 8;
;         float cur[8], prv[8], nxt[8], v[8];
;         unpack8(*(const u32x4*)(p + (size_t)tl * DINP + col), cur);
;         if (pos > 0) unpack8(*(const u32x4*)(p + (size_t)(tl - 1) * DINP + col), prv); else {
; #pragma unroll
;             for (int j = 0; j < 8; ++j) prv[j] = 0.f; }
;         if (pos < L - 1) unpack8(*(const u32x4*)(p + (size_t)(tl + 1) * DINP + col), nxt); else {
; #pragma unroll
;             for (int j = 0; j < 8; ++j) nxt[j] = 0.f; }
;         const f32x4 m0 = *(const f32x4*)(mu + col - PC_R), m1 = *(const f32x4*)(mu + col - PC_R + 4);
; #pragma unroll
;         for (int j = 0; j < 8; ++j) { const float m = j < 4 ? m0[j] : m1[j - 4]; v[j] = cur[j] + m * (0.5f * (prv[j] + nxt[j]) - cur[j]); }
;         if (cg8 < 16) {
; #pragma unroll
;             for (int j = 0; j < 8; ++j) { const float e = __expf(2.f * v[j]); v[j] = 1.f - 2.f * __builtin_amdgcn_rcpf(e + 1.f); }
;         } else if (cg8 >= 32) {
; #pragma unroll
;             for (int j = 0; j < 8; ++j) v[j] = sigm(v[j]);
;         }
;         u32x4 o; o.x = pk2(v[0], v[1]); o.y = pk2(v[2], v[3]); o.z = pk2(v[4], v[5]); o.w = pk2(v[6], v[7]);
;         *(LAS u32x4*)(lin + t * LL + cg8 * 8) = o;
;     }
.LBB0_226:
	s_mov_b32 s42, 0
	s_mov_b64 s[0:1], 0x1c00
.Llin_loop:
	v_add_u32_e32 v22, s42, v125
	v_mul_hi_i32 v0, v22, s96
	v_lshrrev_b32_e32 v23, 31, v0
	v_ashrrev_i32_e32 v0, 3, v0
	v_add_u32_e32 v23, v0, v23
	v_mul_lo_u32 v0, v23, 48
	v_sub_u32_e32 v25, v22, v0
	v_add_u32_e32 v26, s2, v23
	v_lshlrev_b32_e32 v24, 4, v25
	v_add_u32_e32 v0, -1, v26
	v_add_u32_e32 v36, 0xc40, v24
	v_mov_b32_e32 v37, v1
	v_mad_i64_i32 v[28:29], s[6:7], v0, s65, v[36:37]
	v_lshl_add_u64 v[28:29], s[92:93], 0, v[28:29]
	v_lshl_add_u64 v[30:31], v[28:29], 0, s[0:1]
	v_lshl_add_u64 v[32:33], v[30:31], 0, s[0:1]
	global_load_dwordx4 v[2:5], v[30:31], off
	global_load_dwordx4 v[6:9], v[28:29], off
	global_load_dwordx4 v[10:13], v[32:33], off
	v_lshlrev_b32_e32 v0, 5, v25
	v_add_u32_e32 v0, 0xc00, v0
	global_load_dwordx4 v[14:17], v0, s[46:47]
	global_load_dwordx4 v[18:21], v0, s[46:47] offset:16
	v_and_b32_e32 v27, s37, v26
	s_waitcnt vmcnt(0)
	v_cmp_eq_u32_e32 vcc, 0, v27
	s_nop 1
	v_cndmask_b32_e32 v6, v6, v1, vcc
	v_cndmask_b32_e32 v7, v7, v1, vcc
	v_cndmask_b32_e32 v8, v8, v1, vcc
	v_cndmask_b32_e32 v9, v9, v1, vcc
	v_cmp_eq_u32_e32 vcc, s37, v27
	s_nop 1
	v_cndmask_b32_e32 v10, v10, v1, vcc
	v_cndmask_b32_e32 v11, v11, v1, vcc
	v_cndmask_b32_e32 v12, v12, v1, vcc
	v_cndmask_b32_e32 v13, v13, v1, vcc
	v_lshlrev_b32_e32 v36, 16, v6
	v_and_b32_e32 v37, 0xffff0000, v6
	v_lshlrev_b32_e32 v198, 16, v10
	v_and_b32_e32 v199, 0xffff0000, v10
	v_pk_add_f32 v[36:37], v[36:37], v[198:199]
	v_lshlrev_b32_e32 v198, 16, v2
	v_and_b32_e32 v199, 0xffff0000, v2
	v_pk_fma_f32 v[36:37], v[36:37], 0.5, v[198:199] op_sel_hi:[1,0,1] neg_lo:[0,0,1] neg_hi:[0,0,1]
	v_pk_fma_f32 v[28:29], v[14:15], v[36:37], v[198:199]
	v_lshlrev_b32_e32 v36, 16, v7
	v_and_b32_e32 v37, 0xffff0000, v7
	v_lshlrev_b32_e32 v198, 16, v11
	v_and_b32_e32 v199, 0xffff0000, v11
	v_pk_add_f32 v[36:37], v[36:37], v[198:199]
	v_lshlrev_b32_e32 v198, 16, v3
	v_and_b32_e32 v199, 0xffff0000, v3
	v_pk_fma_f32 v[36:37], v[36:37], 0.5, v[198:199] op_sel_hi:[1,0,1] neg_lo:[0,0,1] neg_hi:[0,0,1]
	v_pk_fma_f32 v[30:31], v[16:17], v[36:37], v[198:199]
	v_lshlrev_b32_e32 v36, 16, v8
	v_and_b32_e32 v37, 0xffff0000, v8
	v_lshlrev_b32_e32 v198, 16, v12
	v_and_b32_e32 v199, 0xffff0000, v12
	v_pk_add_f32 v[36:37], v[36:37], v[198:199]
	v_lshlrev_b32_e32 v198, 16, v4
	v_and_b32_e32 v199, 0xffff0000, v4
	v_pk_fma_f32 v[36:37], v[36:37], 0.5, v[198:199] op_sel_hi:[1,0,1] neg_lo:[0,0,1] neg_hi:[0,0,1]
	v_pk_fma_f32 v[32:33], v[18:19], v[36:37], v[198:199]
	v_lshlrev_b32_e32 v36, 16, v9
	v_and_b32_e32 v37, 0xffff0000, v9
	v_lshlrev_b32_e32 v198, 16, v13
	v_and_b32_e32 v199, 0xffff0000, v13
	v_pk_add_f32 v[36:37], v[36:37], v[198:199]
	v_lshlrev_b32_e32 v198, 16, v5
	v_and_b32_e32 v199, 0xffff0000, v5
	v_pk_fma_f32 v[36:37], v[36:37], 0.5, v[198:199] op_sel_hi:[1,0,1] neg_lo:[0,0,1] neg_hi:[0,0,1]
	v_pk_fma_f32 v[34:35], v[20:21], v[36:37], v[198:199]
	v_cmp_gt_u32_e32 vcc, 16, v25
	s_and_saveexec_b64 s[6:7], vcc
	s_cbranch_execz .Llin_c1
	v_add_f32_e32 v36, v28, v28
	v_add_f32_e32 v37, v29, v29
	v_add_f32_e32 v198, v30, v30
	v_add_f32_e32 v199, v31, v31
	v_mul_f32_e32 v36, 0x3fb8aa3b, v36
	v_mul_f32_e32 v37, 0x3fb8aa3b, v37
	v_mul_f32_e32 v198, 0x3fb8aa3b, v198
	v_mul_f32_e32 v199, 0x3fb8aa3b, v199
	v_exp_f32_e32 v36, v36
	v_exp_f32_e32 v37, v37
	v_exp_f32_e32 v198, v198
	v_exp_f32_e32 v199, v199
	v_add_f32_e32 v36, 1.0, v36
	v_add_f32_e32 v37, 1.0, v37
	v_add_f32_e32 v198, 1.0, v198
	v_add_f32_e32 v199, 1.0, v199
	v_rcp_f32_e32 v36, v36
	v_rcp_f32_e32 v37, v37
	v_rcp_f32_e32 v198, v198
	v_rcp_f32_e32 v199, v199
	s_nop 0
	v_fma_f32 v28, v36, -2.0, 1.0
	v_fma_f32 v29, v37, -2.0, 1.0
	v_fma_f32 v30, v198, -2.0, 1.0
	v_fma_f32 v31, v199, -2.0, 1.0
	v_add_f32_e32 v36, v32, v32
	v_add_f32_e32 v37, v33, v33
	v_add_f32_e32 v198, v34, v34
	v_add_f32_e32 v199, v35, v35
	v_mul_f32_e32 v36, 0x3fb8aa3b, v36
	v_mul_f32_e32 v37, 0x3fb8aa3b, v37
	v_mul_f32_e32 v198, 0x3fb8aa3b, v198
	v_mul_f32_e32 v199, 0x3fb8aa3b, v199
	v_exp_f32_e32 v36, v36
	v_exp_f32_e32 v37, v37
	v_exp_f32_e32 v198, v198
	v_exp_f32_e32 v199, v199
	v_add_f32_e32 v36, 1.0, v36
	v_add_f32_e32 v37, 1.0, v37
	v_add_f32_e32 v198, 1.0, v198
	v_add_f32_e32 v199, 1.0, v199
	v_rcp_f32_e32 v36, v36
	v_rcp_f32_e32 v37, v37
	v_rcp_f32_e32 v198, v198
	v_rcp_f32_e32 v199, v199
	s_nop 0
	v_fma_f32 v32, v36, -2.0, 1.0
	v_fma_f32 v33, v37, -2.0, 1.0
	v_fma_f32 v34, v198, -2.0, 1.0
	v_fma_f32 v35, v199, -2.0, 1.0
.Llin_c1:
	s_or_b64 exec, exec, s[6:7]
	v_cmp_lt_u32_e32 vcc, 31, v25
	s_and_saveexec_b64 s[6:7], vcc
	s_cbranch_execz .Llin_c2
	v_mul_f32_e32 v36, 0xbfb8aa3b, v28
	v_mul_f32_e32 v37, 0xbfb8aa3b, v29
	v_mul_f32_e32 v198, 0xbfb8aa3b, v30
	v_mul_f32_e32 v199, 0xbfb8aa3b, v31
	v_exp_f32_e32 v36, v36
	v_exp_f32_e32 v37, v37
	v_exp_f32_e32 v198, v198
	v_exp_f32_e32 v199, v199
	v_add_f32_e32 v36, 1.0, v36
	v_add_f32_e32 v37, 1.0, v37
	v_add_f32_e32 v198, 1.0, v198
	v_add_f32_e32 v199, 1.0, v199
	v_rcp_f32_e32 v28, v36
	v_rcp_f32_e32 v29, v37
	v_rcp_f32_e32 v30, v198
	v_rcp_f32_e32 v31, v199
	v_mul_f32_e32 v36, 0xbfb8aa3b, v32
	v_mul_f32_e32 v37, 0xbfb8aa3b, v33
	v_mul_f32_e32 v198, 0xbfb8aa3b, v34
	v_mul_f32_e32 v199, 0xbfb8aa3b, v35
	v_exp_f32_e32 v36, v36
	v_exp_f32_e32 v37, v37
	v_exp_f32_e32 v198, v198
	v_exp_f32_e32 v199, v199
	v_add_f32_e32 v36, 1.0, v36
	v_add_f32_e32 v37, 1.0, v37
	v_add_f32_e32 v198, 1.0, v198
	v_add_f32_e32 v199, 1.0, v199
	v_rcp_f32_e32 v32, v36
	v_rcp_f32_e32 v33, v37
	v_rcp_f32_e32 v34, v198
	v_rcp_f32_e32 v35, v199
.Llin_c2:
	s_or_b64 exec, exec, s[6:7]
	s_nop 0
	v_cvt_pk_bf16_f32 v28, v28, v29
	v_cvt_pk_bf16_f32 v29, v30, v31
	v_cvt_pk_bf16_f32 v30, v32, v33
	v_cvt_pk_bf16_f32 v31, v34, v35
	v_mul_u32_u24_e32 v0, 0x310, v23
	v_add_u32_e32 v0, v0, v24
	ds_write_b128 v0, v[28:31]
	s_addk_i32 s42, 0x200
	s_cmpk_lg_i32 s42, 0xc00
	s_cbranch_scc1 .Llin_loop

; #define LAS __attribute__((address_space(3)))
; __device__ __forceinline__ unsigned f2bf(float f) { return (unsigned)__builtin_bit_cast(unsigned short, (__bf16)f); }
; __device__ __forceinline__ float sigm(float x) { return __builtin_amdgcn_rcpf(1.0f + __expf(-x)); }
; __device__ __forceinline__ f32x4 mfma16(bf16x8 a, bf16x8 b, f32x4 c) { return __builtin_amdgcn_mfma_f32_16x16x32_bf16(a, b, c, 0, 0, 0); }
; __device__ __forceinline__ void prep_tile64(LAS unsigned char* lds, const Params& P, const MixBufs& B, const bf16_t* sw, int layer, int L, int tile) {
;     ...
; #pragma unroll 1
;     for (int d = 0; d < 2; ++d)
; #pragma unroll 1
;         for (int tt = 0; tt < 2; ++tt) {
;             const int tn = 2 * w + tt, c = tn * 16 + r;
;             const float a0c = P.in[11][(layer * 2 + d) * 256 + c];
;             const bf16_t* wb = sw + 32768 + d * 16384 + (size_t)(tn * 16 + r) * 64 + q * 8;
;             const bf16x8 b0 = *(const bf16x8*)wb, b1 = *(const bf16x8*)(wb + 32);
; #pragma unroll
;             for (int tm = 0; tm < 4; ++tm) {
;                 const LAS bf16_t* ap = lin + (tm * 16 + r) * LL + 128 + d * 64 + q * 8;
;                 f32x4 acc = (f32x4){0.f, 0.f, 0.f, 0.f};
;                 acc = mfma16(*(const LAS bf16x8*)ap, b0, acc); acc = mfma16(*(const LAS bf16x8*)(ap + 32), b1, acc);
; #pragma unroll
;                 for (int jj = 0; jj < 4; ++jj) AS[(d * 64 + tm * 16 + q * 4 + jj) * LA + c] = (bf16_t)f2bf(sigm(a0c + acc[jj]));
;             }
;         }
.LBB0_258:
	s_or_b64 exec, exec, s[0:1]
	v_and_b32_e32 v134, 15, v125
	v_bfe_u32 v2, v125, 4, 2
	v_lshlrev_b32_e32 v0, 4, v2
	v_mul_u32_u24_e32 v141, 0x310, v134
	v_ashrrev_i32_e32 v135, 6, v125
	v_add3_u32 v140, 0, v141, v0
	v_lshl_or_b32 v136, v135, 5, v134
	v_lshlrev_b32_e32 v124, 3, v2
	v_lshl_add_u64 v[10:11], s[94:95], 0, v[0:1]
	v_lshlrev_b32_e32 v142, 2, v2
	v_add_u32_e32 v139, 0x3100, v140
	v_add_u32_e32 v138, 0x6200, v140
	v_add_u32_e32 v137, 0x9300, v140
	s_mov_b32 s16, 0
	s_mov_b64 s[6:7], -1
	s_waitcnt lgkmcnt(0)
	s_barrier
	v_lshlrev_b32_e32 v0, 7, v136
	v_lshl_add_u64 v[2:3], v[10:11], 0, v[0:1]
	s_mov_b64 s[0:1], 0x8000
	v_lshl_add_u64 v[8:9], v[2:3], 0, s[0:1]
	global_load_dwordx4 v[12:15], v[2:3], off
	global_load_dwordx4 v[16:19], v[2:3], off offset:64
	global_load_dwordx4 v[20:23], v[2:3], off offset:2048
	global_load_dwordx4 v[24:27], v[2:3], off offset:2112
	v_add_u32_e32 v6, s76, v136
	v_lshlrev_b32_e32 v6, 2, v6
	global_load_dword v28, v6, s[14:15]
	global_load_dword v29, v6, s[14:15] offset:64
	v_mul_u32_u24_e32 v7, 0x210, v142
	v_lshl_add_u32 v7, v136, 1, v7
	v_add_u32_e32 v7, 0xd800, v7
	ds_read_b128 v[2:5], v140 offset:256
	ds_read_b128 v[198:201], v140 offset:320
	s_waitcnt vmcnt(0)
	s_waitcnt lgkmcnt(1)
	v_mfma_f32_16x16x32_bf16 v[30:33], v[2:5], v[12:15], 0
	v_mfma_f32_16x16x32_bf16 v[34:37], v[2:5], v[20:23], 0
	s_waitcnt lgkmcnt(0)
	v_mfma_f32_16x16x32_bf16 v[30:33], v[198:201], v[16:19], v[30:33]
	v_mfma_f32_16x16x32_bf16 v[34:37], v[198:201], v[24:27], v[34:37]
	s_nop 7
	v_add_f32_e32 v2, v28, v30
	v_add_f32_e32 v3, v28, v31
	v_add_f32_e32 v4, v28, v32
	v_add_f32_e32 v5, v28, v33
	v_add_f32_e32 v198, v29, v34
	v_add_f32_e32 v199, v29, v35
	v_add_f32_e32 v200, v29, v36
	v_add_f32_e32 v201, v29, v37
	v_mul_f32_e32 v2, 0xbfb8aa3b, v2
	v_mul_f32_e32 v3, 0xbfb8aa3b, v3
	v_mul_f32_e32 v4, 0xbfb8aa3b, v4
	v_mul_f32_e32 v5, 0xbfb8aa3b, v5
	v_mul_f32_e32 v198, 0xbfb8aa3b, v198
	v_mul_f32_e32 v199, 0xbfb8aa3b, v199
	v_mul_f32_e32 v200, 0xbfb8aa3b, v200
	v_mul_f32_e32 v201, 0xbfb8aa3b, v201
	v_exp_f32_e32 v2, v2
	v_exp_f32_e32 v3, v3
	v_exp_f32_e32 v4, v4
	v_exp_f32_e32 v5, v5
	v_exp_f32_e32 v198, v198
	v_exp_f32_e32 v199, v199
	v_exp_f32_e32 v200, v200
	v_exp_f32_e32 v201, v201
	v_add_f32_e32 v2, 1.0, v2
	v_add_f32_e32 v3, 1.0, v3
	v_add_f32_e32 v4, 1.0, v4
	v_add_f32_e32 v5, 1.0, v5
	v_add_f32_e32 v198, 1.0, v198
	v_add_f32_e32 v199, 1.0, v199
	v_add_f32_e32 v200, 1.0, v200
	v_add_f32_e32 v201, 1.0, v201
	v_rcp_f32_e32 v2, v2
	v_rcp_f32_e32 v3, v3
	v_rcp_f32_e32 v4, v4
	v_rcp_f32_e32 v5, v5
	v_rcp_f32_e32 v198, v198
	v_rcp_f32_e32 v199, v199
	v_rcp_f32_e32 v200, v200
	v_rcp_f32_e32 v201, v201
	s_nop 0
	v_cvt_pk_bf16_f32 v2, v2, v2
	v_cvt_pk_bf16_f32 v3, v3, v3
	v_cvt_pk_bf16_f32 v4, v4, v4
	v_cvt_pk_bf16_f32 v5, v5, v5
	v_cvt_pk_bf16_f32 v198, v198, v198
	v_cvt_pk_bf16_f32 v199, v199, v199
	v_cvt_pk_bf16_f32 v200, v200, v200
	v_cvt_pk_bf16_f32 v201, v201, v201
	ds_write_b16 v7, v2 offset:0
	ds_write_b16 v7, v3 offset:528
	ds_write_b16 v7, v4 offset:1056
	ds_write_b16 v7, v5 offset:1584
	ds_write_b16 v7, v198 offset:32
	ds_write_b16 v7, v199 offset:560
	ds_write_b16 v7, v200 offset:1088
	ds_write_b16 v7, v201 offset:1616
	ds_read_b128 v[2:5], v140 offset:12800
	ds_read_b128 v[198:201], v140 offset:12864
	s_waitcnt lgkmcnt(1)
	v_mfma_f32_16x16x32_bf16 v[30:33], v[2:5], v[12:15], 0
	v_mfma_f32_16x16x32_bf16 v[34:37], v[2:5], v[20:23], 0
	s_waitcnt lgkmcnt(0)
	v_mfma_f32_16x16x32_bf16 v[30:33], v[198:201], v[16:19], v[30:33]
	v_mfma_f32_16x16x32_bf16 v[34:37], v[198:201], v[24:27], v[34:37]
	s_nop 7
	v_add_f32_e32 v2, v28, v30
	v_add_f32_e32 v3, v28, v31
	v_add_f32_e32 v4, v28, v32
	v_add_f32_e32 v5, v28, v33
	v_add_f32_e32 v198, v29, v34
	v_add_f32_e32 v199, v29, v35
	v_add_f32_e32 v200, v29, v36
	v_add_f32_e32 v201, v29, v37
	v_mul_f32_e32 v2, 0xbfb8aa3b, v2
	v_mul_f32_e32 v3, 0xbfb8aa3b, v3
	v_mul_f32_e32 v4, 0xbfb8aa3b, v4
	v_mul_f32_e32 v5, 0xbfb8aa3b, v5
	v_mul_f32_e32 v198, 0xbfb8aa3b, v198
	v_mul_f32_e32 v199, 0xbfb8aa3b, v199
	v_mul_f32_e32 v200, 0xbfb8aa3b, v200
	v_mul_f32_e32 v201, 0xbfb8aa3b, v201
	v_exp_f32_e32 v2, v2
	v_exp_f32_e32 v3, v3
	v_exp_f32_e32 v4, v4
	v_exp_f32_e32 v5, v5
	v_exp_f32_e32 v198, v198
	v_exp_f32_e32 v199, v199
	v_exp_f32_e32 v200, v200
	v_exp_f32_e32 v201, v201
	v_add_f32_e32 v2, 1.0, v2
	v_add_f32_e32 v3, 1.0, v3
	v_add_f32_e32 v4, 1.0, v4
	v_add_f32_e32 v5, 1.0, v5
	v_add_f32_e32 v198, 1.0, v198
	v_add_f32_e32 v199, 1.0, v199
	v_add_f32_e32 v200, 1.0, v200
	v_add_f32_e32 v201, 1.0, v201
	v_rcp_f32_e32 v2, v2
	v_rcp_f32_e32 v3, v3
	v_rcp_f32_e32 v4, v4
	v_rcp_f32_e32 v5, v5
	v_rcp_f32_e32 v198, v198
	v_rcp_f32_e32 v199, v199
	v_rcp_f32_e32 v200, v200
	v_rcp_f32_e32 v201, v201
	s_nop 0
	v_cvt_pk_bf16_f32 v2, v2, v2
	v_cvt_pk_bf16_f32 v3, v3, v3
	v_cvt_pk_bf16_f32 v4, v4, v4
	v_cvt_pk_bf16_f32 v5, v5, v5
	v_cvt_pk_bf16_f32 v198, v198, v198
	v_cvt_pk_bf16_f32 v199, v199, v199
	v_cvt_pk_bf16_f32 v200, v200, v200
	v_cvt_pk_bf16_f32 v201, v201, v201
	ds_write_b16 v7, v2 offset:8448
	ds_write_b16 v7, v3 offset:8976
	ds_write_b16 v7, v4 offset:9504
	ds_write_b16 v7, v5 offset:10032
	ds_write_b16 v7, v198 offset:8480
	ds_write_b16 v7, v199 offset:9008
	ds_write_b16 v7, v200 offset:9536
	ds_write_b16 v7, v201 offset:10064
	ds_read_b128 v[2:5], v140 offset:25344
	ds_read_b128 v[198:201], v140 offset:25408
	s_waitcnt lgkmcnt(1)
	v_mfma_f32_16x16x32_bf16 v[30:33], v[2:5], v[12:15], 0
	v_mfma_f32_16x16x32_bf16 v[34:37], v[2:5], v[20:23], 0
	s_waitcnt lgkmcnt(0)
; #define LAS __attribute__((address_space(3)))
; __device__ __forceinline__ unsigned f2bf(float f) { return (unsigned)__builtin_bit_cast(unsigned short, (__bf16)f); }
; __device__ __forceinline__ float sigm(float x) { return __builtin_amdgcn_rcpf(1.0f + __expf(-x)); }
; __device__ __forceinline__ f32x4 mfma16(bf16x8 a, bf16x8 b, f32x4 c) { return __builtin_amdgcn_mfma_f32_16x16x32_bf16(a, b, c, 0, 0, 0); }
; __device__ __forceinline__ void prep_tile64(LAS unsigned char* lds, const Params& P, const MixBufs& B, const bf16_t* sw, int layer, int L, int tile) {
;     ...
; #pragma unroll 1
;     for (int d = 0; d < 2; ++d)
; #pragma unroll 1
;         for (int tt = 0; tt < 2; ++tt) {
;             const int tn = 2 * w + tt, c = tn * 16 + r;
;             const float a0c = P.in[11][(layer * 2 + d) * 256 + c];
;             const bf16_t* wb = sw + 32768 + d * 16384 + (size_t)(tn * 16 + r) * 64 + q * 8;
;             const bf16x8 b0 = *(const bf16x8*)wb, b1 = *(const bf16x8*)(wb + 32);
; #pragma unroll
;             for (int tm = 0; tm < 4; ++tm) {
;                 const LAS bf16_t* ap = lin + (tm * 16 + r) * LL + 128 + d * 64 + q * 8;
;                 f32x4 acc = (f32x4){0.f, 0.f, 0.f, 0.f};
;                 acc = mfma16(*(const LAS bf16x8*)ap, b0, acc); acc = mfma16(*(const LAS bf16x8*)(ap + 32), b1, acc);
; #pragma unroll
;                 for (int jj = 0; jj < 4; ++jj) AS[(d * 64 + tm * 16 + q * 4 + jj) * LA + c] = (bf16_t)f2bf(sigm(a0c + acc[jj]));
;             }
;         }
	v_mfma_f32_16x16x32_bf16 v[30:33], v[198:201], v[16:19], v[30:33]
	v_mfma_f32_16x16x32_bf16 v[34:37], v[198:201], v[24:27], v[34:37]
	s_nop 7
	v_add_f32_e32 v2, v28, v30
	v_add_f32_e32 v3, v28, v31
	v_add_f32_e32 v4, v28, v32
	v_add_f32_e32 v5, v28, v33
	v_add_f32_e32 v198, v29, v34
	v_add_f32_e32 v199, v29, v35
	v_add_f32_e32 v200, v29, v36
	v_add_f32_e32 v201, v29, v37
	v_mul_f32_e32 v2, 0xbfb8aa3b, v2
	v_mul_f32_e32 v3, 0xbfb8aa3b, v3
	v_mul_f32_e32 v4, 0xbfb8aa3b, v4
	v_mul_f32_e32 v5, 0xbfb8aa3b, v5
	v_mul_f32_e32 v198, 0xbfb8aa3b, v198
	v_mul_f32_e32 v199, 0xbfb8aa3b, v199
	v_mul_f32_e32 v200, 0xbfb8aa3b, v200
	v_mul_f32_e32 v201, 0xbfb8aa3b, v201
	v_exp_f32_e32 v2, v2
	v_exp_f32_e32 v3, v3
	v_exp_f32_e32 v4, v4
	v_exp_f32_e32 v5, v5
	v_exp_f32_e32 v198, v198
	v_exp_f32_e32 v199, v199
	v_exp_f32_e32 v200, v200
	v_exp_f32_e32 v201, v201
	v_add_f32_e32 v2, 1.0, v2
	v_add_f32_e32 v3, 1.0, v3
	v_add_f32_e32 v4, 1.0, v4
	v_add_f32_e32 v5, 1.0, v5
	v_add_f32_e32 v198, 1.0, v198
	v_add_f32_e32 v199, 1.0, v199
	v_add_f32_e32 v200, 1.0, v200
	v_add_f32_e32 v201, 1.0, v201
	v_rcp_f32_e32 v2, v2
	v_rcp_f32_e32 v3, v3
	v_rcp_f32_e32 v4, v4
	v_rcp_f32_e32 v5, v5
	v_rcp_f32_e32 v198, v198
	v_rcp_f32_e32 v199, v199
	v_rcp_f32_e32 v200, v200
	v_rcp_f32_e32 v201, v201
	s_nop 0
	v_cvt_pk_bf16_f32 v2, v2, v2
	v_cvt_pk_bf16_f32 v3, v3, v3
	v_cvt_pk_bf16_f32 v4, v4, v4
	v_cvt_pk_bf16_f32 v5, v5, v5
	v_cvt_pk_bf16_f32 v198, v198, v198
	v_cvt_pk_bf16_f32 v199, v199, v199
	v_cvt_pk_bf16_f32 v200, v200, v200
	v_cvt_pk_bf16_f32 v201, v201, v201
	ds_write_b16 v7, v2 offset:16896
	ds_write_b16 v7, v3 offset:17424
	ds_write_b16 v7, v4 offset:17952
	ds_write_b16 v7, v5 offset:18480
	ds_write_b16 v7, v198 offset:16928
	ds_write_b16 v7, v199 offset:17456
	ds_write_b16 v7, v200 offset:17984
	ds_write_b16 v7, v201 offset:18512
	ds_read_b128 v[2:5], v140 offset:37888
	ds_read_b128 v[198:201], v140 offset:37952
	s_waitcnt lgkmcnt(1)
	v_mfma_f32_16x16x32_bf16 v[30:33], v[2:5], v[12:15], 0
	v_mfma_f32_16x16x32_bf16 v[34:37], v[2:5], v[20:23], 0
	s_waitcnt lgkmcnt(0)
	v_mfma_f32_16x16x32_bf16 v[30:33], v[198:201], v[16:19], v[30:33]
	v_mfma_f32_16x16x32_bf16 v[34:37], v[198:201], v[24:27], v[34:37]
	s_nop 7
	v_add_f32_e32 v2, v28, v30
	v_add_f32_e32 v3, v28, v31
	v_add_f32_e32 v4, v28, v32
	v_add_f32_e32 v5, v28, v33
	v_add_f32_e32 v198, v29, v34
	v_add_f32_e32 v199, v29, v35
	v_add_f32_e32 v200, v29, v36
	v_add_f32_e32 v201, v29, v37
	v_mul_f32_e32 v2, 0xbfb8aa3b, v2
	v_mul_f32_e32 v3, 0xbfb8aa3b, v3
	v_mul_f32_e32 v4, 0xbfb8aa3b, v4
	v_mul_f32_e32 v5, 0xbfb8aa3b, v5
	v_mul_f32_e32 v198, 0xbfb8aa3b, v198
	v_mul_f32_e32 v199, 0xbfb8aa3b, v199
	v_mul_f32_e32 v200, 0xbfb8aa3b, v200
	v_mul_f32_e32 v201, 0xbfb8aa3b, v201
	v_exp_f32_e32 v2, v2
	v_exp_f32_e32 v3, v3
	v_exp_f32_e32 v4, v4
	v_exp_f32_e32 v5, v5
	v_exp_f32_e32 v198, v198
	v_exp_f32_e32 v199, v199
	v_exp_f32_e32 v200, v200
	v_exp_f32_e32 v201, v201
	v_add_f32_e32 v2, 1.0, v2
	v_add_f32_e32 v3, 1.0, v3
	v_add_f32_e32 v4, 1.0, v4
	v_add_f32_e32 v5, 1.0, v5
	v_add_f32_e32 v198, 1.0, v198
	v_add_f32_e32 v199, 1.0, v199
	v_add_f32_e32 v200, 1.0, v200
	v_add_f32_e32 v201, 1.0, v201
	v_rcp_f32_e32 v2, v2
	v_rcp_f32_e32 v3, v3
	v_rcp_f32_e32 v4, v4
	v_rcp_f32_e32 v5, v5
	v_rcp_f32_e32 v198, v198
	v_rcp_f32_e32 v199, v199
	v_rcp_f32_e32 v200, v200
	v_rcp_f32_e32 v201, v201
	s_nop 0
	v_cvt_pk_bf16_f32 v2, v2, v2
	v_cvt_pk_bf16_f32 v3, v3, v3
	v_cvt_pk_bf16_f32 v4, v4, v4
	v_cvt_pk_bf16_f32 v5, v5, v5
	v_cvt_pk_bf16_f32 v198, v198, v198
	v_cvt_pk_bf16_f32 v199, v199, v199
	v_cvt_pk_bf16_f32 v200, v200, v200
	v_cvt_pk_bf16_f32 v201, v201, v201
	ds_write_b16 v7, v2 offset:25344
	ds_write_b16 v7, v3 offset:25872
	ds_write_b16 v7, v4 offset:26400
	ds_write_b16 v7, v5 offset:26928
	ds_write_b16 v7, v198 offset:25376
	ds_write_b16 v7, v199 offset:25904
	ds_write_b16 v7, v200 offset:26432
	ds_write_b16 v7, v201 offset:26960
	global_load_dwordx4 v[12:15], v[8:9], off
	global_load_dwordx4 v[16:19], v[8:9], off offset:64
	global_load_dwordx4 v[20:23], v[8:9], off offset:2048
	global_load_dwordx4 v[24:27], v[8:9], off offset:2112
	global_load_dword v28, v6, s[14:15] offset:1024
	global_load_dword v29, v6, s[14:15] offset:1088
	v_add_u32_e32 v7, 0x8400, v7
	ds_read_b128 v[2:5], v140 offset:384
	ds_read_b128 v[198:201], v140 offset:448
	s_waitcnt vmcnt(0)
	s_waitcnt lgkmcnt(1)
	v_mfma_f32_16x16x32_bf16 v[30:33], v[2:5], v[12:15], 0
	v_mfma_f32_16x16x32_bf16 v[34:37], v[2:5], v[20:23], 0
	s_waitcnt lgkmcnt(0)
	v_mfma_f32_16x16x32_bf16 v[30:33], v[198:201], v[16:19], v[30:33]
	v_mfma_f32_16x16x32_bf16 v[34:37], v[198:201], v[24:27], v[34:37]
	s_nop 7
	v_add_f32_e32 v2, v28, v30
	v_add_f32_e32 v3, v28, v31
	v_add_f32_e32 v4, v28, v32
	v_add_f32_e32 v5, v28, v33
	v_add_f32_e32 v198, v29, v34
	v_add_f32_e32 v199, v29, v35
	v_add_f32_e32 v200, v29, v36
	v_add_f32_e32 v201, v29, v37
	v_mul_f32_e32 v2, 0xbfb8aa3b, v2
	v_mul_f32_e32 v3, 0xbfb8aa3b, v3
	v_mul_f32_e32 v4, 0xbfb8aa3b, v4
	v_mul_f32_e32 v5, 0xbfb8aa3b, v5
	v_mul_f32_e32 v198, 0xbfb8aa3b, v198
	v_mul_f32_e32 v199, 0xbfb8aa3b, v199
	v_mul_f32_e32 v200, 0xbfb8aa3b, v200
	v_mul_f32_e32 v201, 0xbfb8aa3b, v201
	v_exp_f32_e32 v2, v2
	v_exp_f32_e32 v3, v3
	v_exp_f32_e32 v4, v4
	v_exp_f32_e32 v5, v5
	v_exp_f32_e32 v198, v198
	v_exp_f32_e32 v199, v199
	v_exp_f32_e32 v200, v200
	v_exp_f32_e32 v201, v201
	v_add_f32_e32 v2, 1.0, v2
	v_add_f32_e32 v3, 1.0, v3
	v_add_f32_e32 v4, 1.0, v4
	v_add_f32_e32 v5, 1.0, v5
	v_add_f32_e32 v198, 1.0, v198
	v_add_f32_e32 v199, 1.0, v199
	v_add_f32_e32 v200, 1.0, v200
	v_add_f32_e32 v201, 1.0, v201
	v_rcp_f32_e32 v2, v2
	v_rcp_f32_e32 v3, v3
	v_rcp_f32_e32 v4, v4
	v_rcp_f32_e32 v5, v5
	v_rcp_f32_e32 v198, v198
	v_rcp_f32_e32 v199, v199
	v_rcp_f32_e32 v200, v200
	v_rcp_f32_e32 v201, v201
	s_nop 0
	v_cvt_pk_bf16_f32 v2, v2, v2
	v_cvt_pk_bf16_f32 v3, v3, v3
	v_cvt_pk_bf16_f32 v4, v4, v4
	v_cvt_pk_bf16_f32 v5, v5, v5
	v_cvt_pk_bf16_f32 v198, v198, v198
	v_cvt_pk_bf16_f32 v199, v199, v199
	v_cvt_pk_bf16_f32 v200, v200, v200
	v_cvt_pk_bf16_f32 v201, v201, v201
	ds_write_b16 v7, v2 offset:0
	ds_write_b16 v7, v3 offset:528
	ds_write_b16 v7, v4 offset:1056
	ds_write_b16 v7, v5 offset:1584
	ds_write_b16 v7, v198 offset:32
	ds_write_b16 v7, v199 offset:560
	ds_write_b16 v7, v200 offset:1088
	ds_write_b16 v7, v201 offset:1616
	ds_read_b128 v[2:5], v140 offset:12928
	ds_read_b128 v[198:201], v140 offset:12992
	s_waitcnt lgkmcnt(1)
; #define LAS __attribute__((address_space(3)))
; __device__ __forceinline__ unsigned f2bf(float f) { return (unsigned)__builtin_bit_cast(unsigned short, (__bf16)f); }
; __device__ __forceinline__ float sigm(float x) { return __builtin_amdgcn_rcpf(1.0f + __expf(-x)); }
; __device__ __forceinline__ f32x4 mfma16(bf16x8 a, bf16x8 b, f32x4 c) { return __builtin_amdgcn_mfma_f32_16x16x32_bf16(a, b, c, 0, 0, 0); }
; __device__ __forceinline__ void prep_tile64(LAS unsigned char* lds, const Params& P, const MixBufs& B, const bf16_t* sw, int layer, int L, int tile) {
;     ...
; #pragma unroll 1
;     for (int d = 0; d < 2; ++d)
; #pragma unroll 1
;         for (int tt = 0; tt < 2; ++tt) {
;             const int tn = 2 * w + tt, c = tn * 16 + r;
;             const float a0c = P.in[11][(layer * 2 + d) * 256 + c];
;             const bf16_t* wb = sw + 32768 + d * 16384 + (size_t)(tn * 16 + r) * 64 + q * 8;
;             const bf16x8 b0 = *(const bf16x8*)wb, b1 = *(const bf16x8*)(wb + 32);
; #pragma unroll
;             for (int tm = 0; tm < 4; ++tm) {
;                 const LAS bf16_t* ap = lin + (tm * 16 + r) * LL + 128 + d * 64 + q * 8;
;                 f32x4 acc = (f32x4){0.f, 0.f, 0.f, 0.f};
;                 acc = mfma16(*(const LAS bf16x8*)ap, b0, acc); acc = mfma16(*(const LAS bf16x8*)(ap + 32), b1, acc);
; #pragma unroll
;                 for (int jj = 0; jj < 4; ++jj) AS[(d * 64 + tm * 16 + q * 4 + jj) * LA + c] = (bf16_t)f2bf(sigm(a0c + acc[jj]));
;             }
;         }
;     __syncthreads();
	v_mfma_f32_16x16x32_bf16 v[30:33], v[2:5], v[12:15], 0
	v_mfma_f32_16x16x32_bf16 v[34:37], v[2:5], v[20:23], 0
	s_waitcnt lgkmcnt(0)
	v_mfma_f32_16x16x32_bf16 v[30:33], v[198:201], v[16:19], v[30:33]
	v_mfma_f32_16x16x32_bf16 v[34:37], v[198:201], v[24:27], v[34:37]
	s_nop 7
	v_add_f32_e32 v2, v28, v30
	v_add_f32_e32 v3, v28, v31
	v_add_f32_e32 v4, v28, v32
	v_add_f32_e32 v5, v28, v33
	v_add_f32_e32 v198, v29, v34
	v_add_f32_e32 v199, v29, v35
	v_add_f32_e32 v200, v29, v36
	v_add_f32_e32 v201, v29, v37
	v_mul_f32_e32 v2, 0xbfb8aa3b, v2
	v_mul_f32_e32 v3, 0xbfb8aa3b, v3
	v_mul_f32_e32 v4, 0xbfb8aa3b, v4
	v_mul_f32_e32 v5, 0xbfb8aa3b, v5
	v_mul_f32_e32 v198, 0xbfb8aa3b, v198
	v_mul_f32_e32 v199, 0xbfb8aa3b, v199
	v_mul_f32_e32 v200, 0xbfb8aa3b, v200
	v_mul_f32_e32 v201, 0xbfb8aa3b, v201
	v_exp_f32_e32 v2, v2
	v_exp_f32_e32 v3, v3
	v_exp_f32_e32 v4, v4
	v_exp_f32_e32 v5, v5
	v_exp_f32_e32 v198, v198
	v_exp_f32_e32 v199, v199
	v_exp_f32_e32 v200, v200
	v_exp_f32_e32 v201, v201
	v_add_f32_e32 v2, 1.0, v2
	v_add_f32_e32 v3, 1.0, v3
	v_add_f32_e32 v4, 1.0, v4
	v_add_f32_e32 v5, 1.0, v5
	v_add_f32_e32 v198, 1.0, v198
	v_add_f32_e32 v199, 1.0, v199
	v_add_f32_e32 v200, 1.0, v200
	v_add_f32_e32 v201, 1.0, v201
	v_rcp_f32_e32 v2, v2
	v_rcp_f32_e32 v3, v3
	v_rcp_f32_e32 v4, v4
	v_rcp_f32_e32 v5, v5
	v_rcp_f32_e32 v198, v198
	v_rcp_f32_e32 v199, v199
	v_rcp_f32_e32 v200, v200
	v_rcp_f32_e32 v201, v201
	s_nop 0
	v_cvt_pk_bf16_f32 v2, v2, v2
	v_cvt_pk_bf16_f32 v3, v3, v3
	v_cvt_pk_bf16_f32 v4, v4, v4
	v_cvt_pk_bf16_f32 v5, v5, v5
	v_cvt_pk_bf16_f32 v198, v198, v198
	v_cvt_pk_bf16_f32 v199, v199, v199
	v_cvt_pk_bf16_f32 v200, v200, v200
	v_cvt_pk_bf16_f32 v201, v201, v201
	ds_write_b16 v7, v2 offset:8448
	ds_write_b16 v7, v3 offset:8976
	ds_write_b16 v7, v4 offset:9504
	ds_write_b16 v7, v5 offset:10032
	ds_write_b16 v7, v198 offset:8480
	ds_write_b16 v7, v199 offset:9008
	ds_write_b16 v7, v200 offset:9536
	ds_write_b16 v7, v201 offset:10064
	ds_read_b128 v[2:5], v140 offset:25472
	ds_read_b128 v[198:201], v140 offset:25536
	s_waitcnt lgkmcnt(1)
	v_mfma_f32_16x16x32_bf16 v[30:33], v[2:5], v[12:15], 0
	v_mfma_f32_16x16x32_bf16 v[34:37], v[2:5], v[20:23], 0
	s_waitcnt lgkmcnt(0)
	v_mfma_f32_16x16x32_bf16 v[30:33], v[198:201], v[16:19], v[30:33]
	v_mfma_f32_16x16x32_bf16 v[34:37], v[198:201], v[24:27], v[34:37]
	s_nop 7
	v_add_f32_e32 v2, v28, v30
	v_add_f32_e32 v3, v28, v31
	v_add_f32_e32 v4, v28, v32
	v_add_f32_e32 v5, v28, v33
	v_add_f32_e32 v198, v29, v34
	v_add_f32_e32 v199, v29, v35
	v_add_f32_e32 v200, v29, v36
	v_add_f32_e32 v201, v29, v37
	v_mul_f32_e32 v2, 0xbfb8aa3b, v2
	v_mul_f32_e32 v3, 0xbfb8aa3b, v3
	v_mul_f32_e32 v4, 0xbfb8aa3b, v4
	v_mul_f32_e32 v5, 0xbfb8aa3b, v5
	v_mul_f32_e32 v198, 0xbfb8aa3b, v198
	v_mul_f32_e32 v199, 0xbfb8aa3b, v199
	v_mul_f32_e32 v200, 0xbfb8aa3b, v200
	v_mul_f32_e32 v201, 0xbfb8aa3b, v201
	v_exp_f32_e32 v2, v2
	v_exp_f32_e32 v3, v3
	v_exp_f32_e32 v4, v4
	v_exp_f32_e32 v5, v5
	v_exp_f32_e32 v198, v198
	v_exp_f32_e32 v199, v199
	v_exp_f32_e32 v200, v200
	v_exp_f32_e32 v201, v201
	v_add_f32_e32 v2, 1.0, v2
	v_add_f32_e32 v3, 1.0, v3
	v_add_f32_e32 v4, 1.0, v4
	v_add_f32_e32 v5, 1.0, v5
	v_add_f32_e32 v198, 1.0, v198
	v_add_f32_e32 v199, 1.0, v199
	v_add_f32_e32 v200, 1.0, v200
	v_add_f32_e32 v201, 1.0, v201
	v_rcp_f32_e32 v2, v2
	v_rcp_f32_e32 v3, v3
	v_rcp_f32_e32 v4, v4
	v_rcp_f32_e32 v5, v5
	v_rcp_f32_e32 v198, v198
	v_rcp_f32_e32 v199, v199
	v_rcp_f32_e32 v200, v200
	v_rcp_f32_e32 v201, v201
	s_nop 0
	v_cvt_pk_bf16_f32 v2, v2, v2
	v_cvt_pk_bf16_f32 v3, v3, v3
	v_cvt_pk_bf16_f32 v4, v4, v4
	v_cvt_pk_bf16_f32 v5, v5, v5
	v_cvt_pk_bf16_f32 v198, v198, v198
	v_cvt_pk_bf16_f32 v199, v199, v199
	v_cvt_pk_bf16_f32 v200, v200, v200
	v_cvt_pk_bf16_f32 v201, v201, v201
	ds_write_b16 v7, v2 offset:16896
	ds_write_b16 v7, v3 offset:17424
	ds_write_b16 v7, v4 offset:17952
	ds_write_b16 v7, v5 offset:18480
	ds_write_b16 v7, v198 offset:16928
	ds_write_b16 v7, v199 offset:17456
	ds_write_b16 v7, v200 offset:17984
	ds_write_b16 v7, v201 offset:18512
	ds_read_b128 v[2:5], v140 offset:38016
	ds_read_b128 v[198:201], v140 offset:38080
	s_waitcnt lgkmcnt(1)
	v_mfma_f32_16x16x32_bf16 v[30:33], v[2:5], v[12:15], 0
	v_mfma_f32_16x16x32_bf16 v[34:37], v[2:5], v[20:23], 0
	s_waitcnt lgkmcnt(0)
	v_mfma_f32_16x16x32_bf16 v[30:33], v[198:201], v[16:19], v[30:33]
	v_mfma_f32_16x16x32_bf16 v[34:37], v[198:201], v[24:27], v[34:37]
	s_nop 7
	v_add_f32_e32 v2, v28, v30
	v_add_f32_e32 v3, v28, v31
	v_add_f32_e32 v4, v28, v32
	v_add_f32_e32 v5, v28, v33
	v_add_f32_e32 v198, v29, v34
	v_add_f32_e32 v199, v29, v35
	v_add_f32_e32 v200, v29, v36
	v_add_f32_e32 v201, v29, v37
	v_mul_f32_e32 v2, 0xbfb8aa3b, v2
	v_mul_f32_e32 v3, 0xbfb8aa3b, v3
	v_mul_f32_e32 v4, 0xbfb8aa3b, v4
	v_mul_f32_e32 v5, 0xbfb8aa3b, v5
	v_mul_f32_e32 v198, 0xbfb8aa3b, v198
	v_mul_f32_e32 v199, 0xbfb8aa3b, v199
	v_mul_f32_e32 v200, 0xbfb8aa3b, v200
	v_mul_f32_e32 v201, 0xbfb8aa3b, v201
	v_exp_f32_e32 v2, v2
	v_exp_f32_e32 v3, v3
	v_exp_f32_e32 v4, v4
	v_exp_f32_e32 v5, v5
	v_exp_f32_e32 v198, v198
	v_exp_f32_e32 v199, v199
	v_exp_f32_e32 v200, v200
	v_exp_f32_e32 v201, v201
	v_add_f32_e32 v2, 1.0, v2
	v_add_f32_e32 v3, 1.0, v3
	v_add_f32_e32 v4, 1.0, v4
	v_add_f32_e32 v5, 1.0, v5
	v_add_f32_e32 v198, 1.0, v198
	v_add_f32_e32 v199, 1.0, v199
	v_add_f32_e32 v200, 1.0, v200
	v_add_f32_e32 v201, 1.0, v201
	v_rcp_f32_e32 v2, v2
	v_rcp_f32_e32 v3, v3
	v_rcp_f32_e32 v4, v4
	v_rcp_f32_e32 v5, v5
	v_rcp_f32_e32 v198, v198
	v_rcp_f32_e32 v199, v199
	v_rcp_f32_e32 v200, v200
	v_rcp_f32_e32 v201, v201
	s_nop 0
	v_cvt_pk_bf16_f32 v2, v2, v2
	v_cvt_pk_bf16_f32 v3, v3, v3
	v_cvt_pk_bf16_f32 v4, v4, v4
	v_cvt_pk_bf16_f32 v5, v5, v5
	v_cvt_pk_bf16_f32 v198, v198, v198
	v_cvt_pk_bf16_f32 v199, v199, v199
	v_cvt_pk_bf16_f32 v200, v200, v200
	v_cvt_pk_bf16_f32 v201, v201, v201
	ds_write_b16 v7, v2 offset:25344
	ds_write_b16 v7, v3 offset:25872
	ds_write_b16 v7, v4 offset:26400
	ds_write_b16 v7, v5 offset:26928
	ds_write_b16 v7, v198 offset:25376
	ds_write_b16 v7, v199 offset:25904
	ds_write_b16 v7, v200 offset:26432
	ds_write_b16 v7, v201 offset:26960
	v_and_b32_e32 v58, 31, v125
	v_lshlrev_b32_e32 v0, 5, v58
	s_waitcnt lgkmcnt(0)
	s_barrier
; #define LD8F(dst, ptr) do { const f32x4 a_ = *(const f32x4*)(ptr), b_ = *(const f32x4*)((ptr) + 4); dst[0] = a_[0]; dst[1] = a_[1]; dst[2] = a_[2]; dst[3] = a_[3]; dst[4] = b_[0]; dst[5] = b_[1]; dst[6] = b_[2]; dst[7] = b_[3]; } while (0)
; __device__ __forceinline__ void prep_tile64(LAS unsigned char* lds, const Params& P, const MixBufs& B, const bf16_t* sw, int layer, int L, int tile) {
;     ...
;     {
;         const int c0 = (tid & 31) * 8, head = (tid & 31) >> 3;
;         float mr_[8], mk_[8], mv_[8], kkc[8], kac[8], rkc[8];
;     ...
;         LD8F(mr_, mu + c0); LD8F(mk_, mu + 256 + c0); LD8F(mv_, mu + 512 + c0);
;         LD8F(kkc, P.in[14] + layer * 256 + c0); LD8F(kac, P.in[15] + layer * 256 + c0); LD8F(rkc, P.in[16] + layer * 256 + c0);
;     ...
;         u32x4 nx[9], cu[9];
;         const u32x4 Z = (u32x4){0u, 0u, 0u, 0u};
;     ...
;         EL_LOAD(nx, 0);
	global_load_dwordx4 v[4:7], v0, s[46:47] offset:16
	global_load_dwordx4 v[8:11], v0, s[46:47]
	global_load_dwordx4 v[12:15], v0, s[46:47] offset:1040
	global_load_dwordx4 v[16:19], v0, s[46:47] offset:1024
	global_load_dwordx4 v[20:23], v0, s[46:47] offset:2064
	global_load_dwordx4 v[24:27], v0, s[46:47] offset:2048
	global_load_dwordx4 v[28:31], v0, s[44:45] offset:16
	global_load_dwordx4 v[32:35], v0, s[44:45]
	global_load_dwordx4 v[36:39], v0, s[90:91] offset:16
	global_load_dwordx4 v[40:43], v0, s[90:91]
	v_readlane_b32 s0, v247, 63
	v_readlane_b32 s1, v246, 0
	s_nop 4
	global_load_dwordx4 v[44:47], v0, s[0:1] offset:16
	global_load_dwordx4 v[48:51], v0, s[0:1]
	v_ashrrev_i32_e32 v0, 5, v125
	v_add_u32_e32 v59, s2, v0
	v_mov_b64_e32 v[2:3], s[92:93]
	v_mad_i64_i32 v[2:3], s[0:1], v59, s65, v[2:3]
	v_lshlrev_b32_e32 v0, 4, v58
	v_lshl_add_u64 v[56:57], v[2:3], 0, v[0:1]
	global_load_dwordx4 v[104:107], v[56:57], off offset:1600
	global_load_dwordx4 v[52:55], v[56:57], off offset:2112
	global_load_dwordx4 v[96:99], v[56:57], off offset:2624
	v_sub_u32_e32 v2, 0, v59
	v_max_i32_e32 v2, v59, v2
	v_mul_hi_u32 v3, v2, v215
	v_mul_lo_u32 v3, v3, s36
	v_sub_u32_e32 v2, v2, v3
	v_subrev_u32_e32 v3, s36, v2
	v_cmp_le_u32_e32 vcc, s36, v2
	v_ashrrev_i32_e32 v0, 31, v59
	v_mov_b32_e32 v70, v1
	v_cndmask_b32_e32 v2, v2, v3, vcc
	v_subrev_u32_e32 v3, s36, v2
	v_cmp_le_u32_e32 vcc, s36, v2
	v_mov_b32_e32 v71, v1
	v_mov_b32_e32 v68, v1
	v_cndmask_b32_e32 v2, v2, v3, vcc
	v_xor_b32_e32 v2, v2, v0
	v_sub_u32_e32 v59, v2, v0
	v_mov_b32_e32 v69, v1
	v_mov_b64_e32 v[114:115], v[70:71]
	v_cmp_lt_i32_e64 s[0:1], 0, v59
	v_mov_b64_e32 v[112:113], v[68:69]
	s_and_saveexec_b64 s[6:7], s[0:1]
	s_cbranch_execz .LBB0_264
	v_add_co_u32_e32 v2, vcc, 0xfffff000, v56
	s_nop 1
	v_addc_co_u32_e32 v3, vcc, -1, v57, vcc
	global_load_dwordx4 v[112:115], v[2:3], off offset:-1472
